# final RMSNorm phase: norm weights loaded once before the row loop, 8 stores per row streamed without the per-store vmcnt(0) (v010 base)
# baseline (speedup 1.0000x reference)
; __global__ void __launch_bounds__(512, 2) fwd_megakernel(Params p_unused) {
;     ...
;   if (PHASES & (1 << 11)) {
;   PHASE_BEGIN()
;   for (int m = gw; m < MTOK; m += NGW) {
;     f32x4v* xr = (f32x4v*)(p.out + (size_t)m * DM) + lane; f32x4v v[8]; float s = 0.f;
; #pragma unroll
;     for (int j = 0; j < 8; ++j) { v[j] = xr[64 * j]; s += (v[j].x * v[j].x + v[j].y * v[j].y) + (v[j].z * v[j].z + v[j].w * v[j].w); }
;     const float rstd = rsqrtf(wave_sum(s) * (1.f / DM) + EPS);
; #pragma unroll
;     for (int j = 0; j < 8; ++j) { const f32x4v w = *(const f32x4v*)(p.final_norm_w + 4 * (lane + 64 * j)); xr[64 * j] = v[j] * rstd * w; }
.LBB0_953:
	s_or_b64 exec, exec, s[2:3]
	s_waitcnt lgkmcnt(0)
	s_barrier
	s_nop 0
	v_readfirstlane_b32 s0, v194
	s_ashr_i32 s1, s0, 6
	s_add_i32 s0, s1, s73
	s_cmpk_lt_i32 s0, 0x4000
	s_cbranch_scc0 .LBB0_956
	v_cmp_lt_i32_e32 vcc, v168, v162
	s_load_dwordx4 s[4:7], s[86:87], 0xb8
	v_and_b32_e32 v0, 63, v194
	v_cndmask_b32_e32 v1, v195, v168, vcc
	v_cmp_lt_i32_e32 vcc, v167, v162
	v_lshlrev_b32_e32 v12, 2, v1
	v_lshlrev_b32_e32 v10, 4, v0
	v_cndmask_b32_e32 v1, v195, v167, vcc
	v_cmp_lt_i32_e32 vcc, v166, v162
	v_lshlrev_b32_e32 v13, 2, v1
	v_mov_b32_e32 v11, 0
	v_cndmask_b32_e32 v1, v195, v166, vcc
	v_cmp_lt_i32_e32 vcc, v165, v162
	v_lshlrev_b32_e32 v14, 2, v1
	s_ashr_i32 s8, s73, 31
	v_cndmask_b32_e32 v1, v195, v165, vcc
	v_cmp_lt_i32_e32 vcc, v164, v162
	v_lshlrev_b32_e32 v15, 2, v1
	s_mov_b64 s[2:3], 0x1000
	v_cndmask_b32_e32 v1, v195, v164, vcc
	v_cmp_lt_i32_e32 vcc, v163, v162
	v_lshlrev_b32_e32 v16, 2, v1
	v_mov_b32_e32 v18, 0x358637bd
	v_cndmask_b32_e32 v1, v195, v163, vcc
	v_lshlrev_b32_e32 v17, 2, v1
	s_waitcnt lgkmcnt(0)
	v_lshl_add_u64 v[0:1], s[4:5], 0, v[10:11]
	s_mov_b64 s[4:5], 0x1400
	v_lshl_add_u64 v[4:5], v[0:1], 0, s[4:5]
	s_mov_b64 s[4:5], 0x1800
	v_lshl_add_u64 v[6:7], v[0:1], 0, s[4:5]
	s_mov_b64 s[4:5], 0x1c00
	v_lshl_add_u64 v[8:9], v[0:1], 0, s[4:5]
	s_ashr_i32 s5, s1, 31
	s_add_u32 s4, s1, s73
	s_addc_u32 s5, s5, s8
	s_lshl_b64 s[4:5], s[4:5], 13
	s_add_u32 s4, s6, s4
	s_addc_u32 s5, s7, s5
	v_lshl_add_u64 v[10:11], s[4:5], 0, v[10:11]
	s_ashr_i32 s75, s74, 31
	v_lshl_add_u64 v[2:3], v[0:1], 0, s[2:3]
	v_lshl_add_u64 v[10:11], v[10:11], 0, s[2:3]
	s_lshl_b64 s[2:3], s[74:75], 13
	s_mov_b32 s1, 0x800000
	global_load_dwordx4 v[96:99], v[0:1], off
	global_load_dwordx4 v[100:103], v[0:1], off offset:1024
	global_load_dwordx4 v[104:107], v[0:1], off offset:2048
	global_load_dwordx4 v[108:111], v[0:1], off offset:3072
	global_load_dwordx4 v[112:115], v[2:3], off
	global_load_dwordx4 v[116:119], v[4:5], off
	global_load_dwordx4 v[120:123], v[6:7], off
	global_load_dwordx4 v[124:127], v[8:9], off
; __global__ void __launch_bounds__(512, 2) fwd_megakernel(Params p_unused) {
;     ...
;   for (int m = gw; m < MTOK; m += NGW) {
;     f32x4v* xr = (f32x4v*)(p.out + (size_t)m * DM) + lane; f32x4v v[8]; float s = 0.f;
; #pragma unroll
;     for (int j = 0; j < 8; ++j) { v[j] = xr[64 * j]; s += (v[j].x * v[j].x + v[j].y * v[j].y) + (v[j].z * v[j].z + v[j].w * v[j].w); }
;     const float rstd = rsqrtf(wave_sum(s) * (1.f / DM) + EPS);
; #pragma unroll
;     for (int j = 0; j < 8; ++j) { const f32x4v w = *(const f32x4v*)(p.final_norm_w + 4 * (lane + 64 * j)); xr[64 * j] = v[j] * rstd * w; }
;   }
.LBB0_955:
	global_load_dwordx4 v[20:23], v[10:11], off offset:-4096
	global_load_dwordx4 v[24:27], v[10:11], off offset:-3072
	global_load_dwordx4 v[28:31], v[10:11], off offset:-2048
	global_load_dwordx4 v[32:35], v[10:11], off
	global_load_dwordx4 v[36:39], v[10:11], off offset:-1024
	global_load_dwordx4 v[40:43], v[10:11], off offset:1024
	global_load_dwordx4 v[44:47], v[10:11], off offset:3072
	global_load_dwordx4 v[48:51], v[10:11], off offset:2048
	s_add_i32 s0, s0, s74
	s_cmpk_gt_i32 s0, 0x3fff
	s_waitcnt vmcnt(7)
	v_mov_b32_e32 v58, v21
	s_waitcnt vmcnt(6)
	v_mov_b32_e32 v59, v25
	v_mov_b32_e32 v62, v23
	v_mov_b32_e32 v63, v27
	v_mov_b32_e32 v56, v20
	v_mov_b32_e32 v57, v24
	v_mov_b32_e32 v60, v22
	v_mov_b32_e32 v61, v26
	s_waitcnt vmcnt(5)
	v_pk_mul_f32 v[64:65], v[30:31], v[30:31]
	v_pk_mul_f32 v[66:67], v[28:29], v[28:29]
	v_pk_mul_f32 v[58:59], v[58:59], v[58:59]
	v_pk_mul_f32 v[62:63], v[62:63], v[62:63]
	v_pk_mov_b32 v[80:81], v[66:67], v[64:65] op_sel:[1,0]
	v_mov_b32_e32 v67, v65
	v_pk_fma_f32 v[56:57], v[56:57], v[56:57], v[58:59]
	v_pk_fma_f32 v[58:59], v[60:61], v[60:61], v[62:63]
	s_waitcnt vmcnt(3)
	v_mul_f32_e32 v68, v37, v37
	v_mul_f32_e32 v70, v39, v39
	v_pk_add_f32 v[60:61], v[80:81], v[66:67]
	v_pk_add_f32 v[56:57], v[56:57], v[58:59]
	v_mul_f32_e32 v19, v32, v32
	v_mul_f32_e32 v79, v33, v33
	v_mul_f32_e32 v82, v34, v34
	v_mul_f32_e32 v83, v35, v35
	v_pk_fma_f32 v[64:65], v[36:37], v[36:37], v[68:69] op_sel_hi:[1,1,0]
	v_pk_fma_f32 v[68:69], v[38:39], v[38:39], v[70:71] op_sel_hi:[1,1,0]
	v_pk_add_f32 v[58:59], v[60:61], v[60:61] op_sel:[0,1] op_sel_hi:[1,0]
	v_pk_add_f32 v[56:57], v[56:57], v[56:57] op_sel:[0,1] op_sel_hi:[1,0]
	s_waitcnt vmcnt(2)
	v_pk_mul_f32 v[72:73], v[42:43], v[42:43]
	v_pk_mul_f32 v[74:75], v[40:41], v[40:41]
	v_mov_b32_e32 v65, v82
	v_mov_b32_e32 v69, v83
	v_mov_b32_e32 v59, v79
	v_mov_b32_e32 v57, v19
	v_pk_mov_b32 v[70:71], v[74:75], v[72:73] op_sel:[1,0]
	v_mov_b32_e32 v75, v73
	v_pk_add_f32 v[60:61], v[64:65], v[68:69]
	v_pk_add_f32 v[56:57], v[56:57], v[58:59]
	s_waitcnt vmcnt(0)
	v_mul_f32_e32 v76, v49, v49
	v_mul_f32_e32 v78, v51, v51
	v_pk_add_f32 v[62:63], v[70:71], v[74:75]
	v_pk_add_f32 v[56:57], v[56:57], v[60:61]
	v_mul_f32_e32 v84, v44, v44
	v_mul_f32_e32 v85, v45, v45
	v_mul_f32_e32 v86, v46, v46
	v_mul_f32_e32 v87, v47, v47
	v_pk_fma_f32 v[72:73], v[48:49], v[48:49], v[76:77] op_sel_hi:[1,1,0]
	v_pk_fma_f32 v[76:77], v[50:51], v[50:51], v[78:79] op_sel_hi:[1,1,0]
	v_pk_add_f32 v[62:63], v[62:63], v[62:63] op_sel:[0,1] op_sel_hi:[1,0]
	v_pk_add_f32 v[56:57], v[56:57], v[56:57] op_sel:[0,1] op_sel_hi:[1,0]
	v_mov_b32_e32 v73, v86
	v_mov_b32_e32 v77, v87
	v_mov_b32_e32 v63, v85
	v_mov_b32_e32 v57, v84
	v_pk_add_f32 v[64:65], v[72:73], v[76:77]
	v_pk_add_f32 v[56:57], v[56:57], v[62:63]
	s_nop 0
	v_pk_add_f32 v[56:57], v[56:57], v[64:65]
	s_nop 0
	v_add_f32_e32 v19, v56, v57
	ds_bpermute_b32 v56, v12, v19
	s_waitcnt lgkmcnt(0)
	v_add_f32_e32 v19, v19, v56
	ds_bpermute_b32 v56, v13, v19
	s_waitcnt lgkmcnt(0)
	v_add_f32_e32 v19, v19, v56
	ds_bpermute_b32 v56, v14, v19
	s_waitcnt lgkmcnt(0)
	v_add_f32_e32 v19, v19, v56
	ds_bpermute_b32 v56, v15, v19
	s_waitcnt lgkmcnt(0)
	v_add_f32_e32 v19, v19, v56
	ds_bpermute_b32 v56, v16, v19
	s_waitcnt lgkmcnt(0)
	v_add_f32_e32 v19, v19, v56
	ds_bpermute_b32 v56, v17, v19
	s_waitcnt lgkmcnt(0)
	v_add_f32_e32 v19, v19, v56
	v_fmamk_f32 v19, v19, 0x3a000000, v18
	v_mul_f32_e32 v56, 0x4b800000, v19
	v_cmp_gt_f32_e32 vcc, s1, v19
	s_nop 1
	v_cndmask_b32_e32 v19, v19, v56, vcc
	v_rsq_f32_e32 v19, v19
	s_nop 0
	v_mul_f32_e32 v56, 0x45800000, v19
	v_cndmask_b32_e32 v56, v19, v56, vcc
	v_pk_mul_f32 v[20:21], v[56:57], v[20:21] op_sel_hi:[0,1]
	v_pk_mul_f32 v[22:23], v[56:57], v[22:23] op_sel_hi:[0,1]
	v_pk_mul_f32 v[22:23], v[22:23], v[98:99]
	v_pk_mul_f32 v[20:21], v[20:21], v[96:97]
	global_store_dwordx4 v[10:11], v[20:23], off offset:-4096
	v_pk_mul_f32 v[26:27], v[56:57], v[26:27] op_sel_hi:[0,1]
	v_pk_mul_f32 v[24:25], v[56:57], v[24:25] op_sel_hi:[0,1]
	v_pk_mul_f32 v[52:53], v[24:25], v[100:101]
	v_pk_mul_f32 v[54:55], v[26:27], v[102:103]
	global_store_dwordx4 v[10:11], v[52:55], off offset:-3072
	v_pk_mul_f32 v[24:25], v[56:57], v[30:31] op_sel_hi:[0,1]
	v_pk_mul_f32 v[26:27], v[56:57], v[28:29] op_sel_hi:[0,1]
	v_pk_mul_f32 v[20:21], v[26:27], v[104:105]
	v_pk_mul_f32 v[22:23], v[24:25], v[106:107]
	global_store_dwordx4 v[10:11], v[20:23], off offset:-2048
	v_pk_mul_f32 v[24:25], v[56:57], v[38:39] op_sel_hi:[0,1]
	v_pk_mul_f32 v[26:27], v[56:57], v[36:37] op_sel_hi:[0,1]
	v_pk_mul_f32 v[52:53], v[26:27], v[108:109]
	v_pk_mul_f32 v[54:55], v[24:25], v[110:111]
	global_store_dwordx4 v[10:11], v[52:55], off offset:-1024
	v_pk_mul_f32 v[24:25], v[56:57], v[34:35] op_sel_hi:[0,1]
	v_pk_mul_f32 v[26:27], v[56:57], v[32:33] op_sel_hi:[0,1]
	v_pk_mul_f32 v[20:21], v[26:27], v[112:113]
	v_pk_mul_f32 v[22:23], v[24:25], v[114:115]
	global_store_dwordx4 v[10:11], v[20:23], off
	v_pk_mul_f32 v[24:25], v[56:57], v[42:43] op_sel_hi:[0,1]
	v_pk_mul_f32 v[26:27], v[56:57], v[40:41] op_sel_hi:[0,1]
	v_pk_mul_f32 v[52:53], v[26:27], v[116:117]
	v_pk_mul_f32 v[54:55], v[24:25], v[118:119]
	global_store_dwordx4 v[10:11], v[52:55], off offset:1024
	v_pk_mul_f32 v[24:25], v[56:57], v[50:51] op_sel_hi:[0,1]
	v_pk_mul_f32 v[26:27], v[56:57], v[48:49] op_sel_hi:[0,1]
	v_pk_mul_f32 v[20:21], v[26:27], v[120:121]
	v_pk_mul_f32 v[22:23], v[24:25], v[122:123]
	global_store_dwordx4 v[10:11], v[20:23], off offset:2048
	v_pk_mul_f32 v[24:25], v[56:57], v[46:47] op_sel_hi:[0,1]
	v_pk_mul_f32 v[26:27], v[56:57], v[44:45] op_sel_hi:[0,1]
	v_pk_mul_f32 v[52:53], v[26:27], v[124:125]
	v_pk_mul_f32 v[54:55], v[24:25], v[126:127]
	global_store_dwordx4 v[10:11], v[52:55], off offset:3072
	v_lshl_add_u64 v[10:11], v[10:11], 0, s[2:3]
	s_cbranch_scc0 .LBB0_955
